# sample-attn: LDS-DMA of step i+2 issued row-by-row inside the staging conversion, next-unit Q load hoisted to step top
# baseline (speedup 1.0000x reference)
.LBB0_1863:
	s_and_b32 s84, s78, 7
	s_cmp_lg_u32 s84, 7
	s_cselect_b64 s[84:85], -1, 0
	s_add_i32 s86, s78, 1
	s_cmp_ge_i32 s86, s62
	s_cselect_b64 s[86:87], -1, 0
	s_or_b64 s[84:85], s[84:85], s[86:87]
	s_nor_b64 s[84:85], s[0:1], s[84:85]
	s_and_saveexec_b64 s[86:87], s[84:85]
	s_cbranch_execz .Lsa_noq
	s_lshr_b32 s92, s78, 3
	s_add_i32 s92, s92, 1
	s_mul_i32 s93, s92, s24
	s_add_i32 s93, s93, s25
	s_ashr_i32 s93, s93, 3
	s_and_b32 s93, s93, -4
	v_add_u32_e32 v147, s93, v190
	v_ashrrev_i32_e32 v149, 31, v147
	v_lshl_or_b32 v147, v147, 3, v170
	v_mad_u64_u32 v[150:151], s[88:89], v147, s33, v[172:173]
	v_mad_i32_i24 v151, v149, s33, v151
	global_load_dwordx4 v[178:181], v[150:151], off
.Lsa_noq:
	s_mov_b64 exec, s[86:87]
	s_add_i32 s46, s78, 2
	s_min_i32 s80, s46, s63
	s_ashr_i32 s46, s80, 3
	s_mul_i32 s46, s46, s24
	s_add_i32 s46, s46, s25
	s_lshl_b32 s46, s46, 2
	s_bfe_u32 s48, s80, 0x20001
	s_or_b32 s48, s46, s48
	s_ashr_i32 s49, s48, 31
	s_and_b32 s47, s78, 7
	s_lshl_b64 s[48:49], s[48:49], 2
	s_add_u32 s48, s18, s48
	s_addc_u32 s49, s19, s49
	s_load_dword s46, s[48:49], 0x0
	s_waitcnt lgkmcnt(0)
	s_cmp_lg_u32 s47, 0
	v_mov_b32_e32 v212, v148
	v_mov_b32_e32 v213, v146
	s_cbranch_scc1 .LBB0_1865
	v_mov_b32_e32 v212, 0
	v_mov_b32_e32 v213, 0xf149f2ca
	v_mov_b32_e32 v138, 0
	v_mov_b32_e32 v139, v212
	v_mov_b32_e32 v140, v212
	v_mov_b32_e32 v141, v212
	v_mov_b32_e32 v130, 0
	v_mov_b32_e32 v131, v212
	v_mov_b32_e32 v132, v212
	v_mov_b32_e32 v133, v212
	v_mov_b32_e32 v142, 0
	v_mov_b32_e32 v143, v212
	v_mov_b32_e32 v144, v212
	v_mov_b32_e32 v145, v212
	v_mov_b32_e32 v134, 0
	v_mov_b32_e32 v135, v212
	v_mov_b32_e32 v136, v212
	v_mov_b32_e32 v137, v212

.LBB0_1875:
	s_waitcnt vmcnt(0)
	s_barrier
	s_ashr_i32 s89, s46, 31
	s_mov_b32 s88, s46
	s_lshl_b64 s[88:89], s[88:89], 7
	s_lshl_b32 s90, s80, 6
	s_and_b32 s90, s90, 64
	s_or_b32 s88, s88, s90
	s_lshl_b64 s[90:91], s[88:89], 10
	s_lshl_b64 s[88:89], s[88:89], 7
	v_lshl_add_u64 v[204:205], v[158:159], 0, s[90:91]
	ds_read_b128 v[150:153], v169
	ds_read_b128 v[154:157], v169 offset:8192
	ds_read_b128 v[196:199], v169 offset:16384
	ds_read_b128 v[200:203], v169 offset:24576
	s_waitcnt lgkmcnt(3)
	v_cvt_pk_bf16_f32 v150, v150, v151
	v_cvt_pk_bf16_f32 v151, v152, v153
	ds_write_b64 v171, v[150:151]
	v_lshl_add_u64 v[214:215], v[204:205], 0, s[20:21]
	s_mov_b32 m0, s54
	s_nop 0
	global_load_lds_dwordx4 v[214:215], off
	s_waitcnt lgkmcnt(3)
	v_cvt_pk_bf16_f32 v150, v154, v155
	v_cvt_pk_bf16_f32 v151, v156, v157
	ds_write_b64 v171, v[150:151] offset:4224
	v_lshl_add_u64 v[214:215], v[204:205], 0, s[30:31]
	s_mov_b32 m0, s55
	s_nop 0
	global_load_lds_dwordx4 v[214:215], off
	s_waitcnt lgkmcnt(3)
	v_cvt_pk_bf16_f32 v150, v196, v197
	v_cvt_pk_bf16_f32 v151, v198, v199
	ds_write_b64 v171, v[150:151] offset:8448
	v_lshl_add_u64 v[214:215], v[204:205], 0, s[34:35]
	s_mov_b32 m0, s56
	s_nop 0
	global_load_lds_dwordx4 v[214:215], off
	s_waitcnt lgkmcnt(3)
	v_cvt_pk_bf16_f32 v150, v200, v201
	v_cvt_pk_bf16_f32 v151, v202, v203
	ds_write_b64 v171, v[150:151] offset:12672
	v_lshl_add_u64 v[214:215], v[204:205], 0, s[36:37]
	s_mov_b32 m0, s57
	s_nop 0
	global_load_lds_dwordx4 v[214:215], off
	ds_read_b128 v[150:153], v169 offset:32768
	ds_read_b128 v[154:157], v169 offset:40960
	ds_read_b128 v[196:199], v169 offset:49152
	ds_read_b128 v[200:203], v169 offset:57344
	s_waitcnt lgkmcnt(3)
	v_cvt_pk_bf16_f32 v150, v150, v151
	v_cvt_pk_bf16_f32 v151, v152, v153
	ds_write_b64 v171, v[150:151] offset:16896
	v_lshl_add_u64 v[214:215], v[204:205], 0, s[38:39]
	s_mov_b32 m0, s58
	s_nop 0
	global_load_lds_dwordx4 v[214:215], off
	s_waitcnt lgkmcnt(3)
	v_cvt_pk_bf16_f32 v150, v154, v155
	v_cvt_pk_bf16_f32 v151, v156, v157
	ds_write_b64 v171, v[150:151] offset:21120
	v_lshl_add_u64 v[214:215], v[204:205], 0, s[40:41]
	s_mov_b32 m0, s59
	s_nop 0
	global_load_lds_dwordx4 v[214:215], off
	s_waitcnt lgkmcnt(3)
	v_cvt_pk_bf16_f32 v150, v196, v197
	v_cvt_pk_bf16_f32 v151, v198, v199
	ds_write_b64 v171, v[150:151] offset:25344
	v_lshl_add_u64 v[214:215], v[204:205], 0, s[42:43]
	s_mov_b32 m0, s60
	s_nop 0
	global_load_lds_dwordx4 v[214:215], off
	s_waitcnt lgkmcnt(3)
	v_cvt_pk_bf16_f32 v150, v200, v201
	v_cvt_pk_bf16_f32 v151, v202, v203
	ds_write_b64 v171, v[150:151] offset:29568
	v_lshl_add_u64 v[214:215], v[204:205], 0, s[44:45]
	s_mov_b32 m0, s61
	s_nop 0
	global_load_lds_dwordx4 v[214:215], off
	v_lshlrev_b32_e32 v237, 4, v230
	v_or_b32_e32 v237, 0x10000, v237
	ds_read_b128 v[150:153], v237
	s_waitcnt lgkmcnt(0)
	v_cvt_pk_bf16_f32 v150, v150, v151
	v_cvt_pk_bf16_f32 v151, v152, v153
	ds_write_b64 v182, v[150:151]
	v_lshl_add_u64 v[214:215], v[160:161], 0, s[88:89]
	s_mov_b32 m0, s28
	v_and_b32_e32 v149, 0xffff0000, v150
	global_load_lds_dwordx4 v[214:215], off
	v_lshlrev_b32_e32 v147, 16, v150
	v_mul_f32_e32 v149, v149, v149
	v_fmac_f32_e32 v149, v147, v147
	v_and_b32_e32 v147, 0xffff0000, v151
	v_lshlrev_b32_e32 v150, 16, v151
	v_mul_f32_e32 v147, v147, v147
	v_fmac_f32_e32 v147, v150, v150
	v_add_f32_e32 v147, v149, v147
	s_nop 1
	v_add_f32_dpp v147, v147, v147 quad_perm:[1,0,3,2] row_mask:0xf bank_mask:0xf bound_ctrl:1
	s_nop 1
	v_add_f32_dpp v147, v147, v147 quad_perm:[2,3,0,1] row_mask:0xf bank_mask:0xf bound_ctrl:1
	s_nop 1
	v_mov_b32_dpp v149, v147 row_half_mirror row_mask:0xf bank_mask:0xf bound_ctrl:1
	s_and_saveexec_b64 s[50:51], s[2:3]
	v_add_f32_e32 v147, v147, v149
	ds_write_b32 v189, v147
	s_or_b64 exec, exec, s[50:51]
	s_add_i32 s78, s78, 1
	s_bitcmp1_b32 s78, 3
	s_cselect_b32 s92, 0x1800, 0
	s_and_saveexec_b64 s[86:87], s[84:85]
	v_add_u32_e32 v147, s92, v191
	ds_write_b128 v147, v[178:181]
	s_mov_b64 exec, s[86:87]
	s_waitcnt lgkmcnt(0)
	s_barrier
	s_cmp_lg_u32 s78, s79
	s_cbranch_scc1 .LBB0_1863
